# plus: SSD C.H products and xs-fragment prefetch interleaved into the P VALU shadow with counted LDS waits; Res epilogue slot refill ahead of stores
# speedup vs baseline: 1.0216x; 1.0013x over previous
; #define LAS __attribute__((address_space(3)))
; __device__ __forceinline__ unsigned pk2(float lo, float hi) { return pg8::cvt_pk_bf16(lo, hi); }
; #define MFMA16(a, b, c) __builtin_amdgcn_mfma_f32_16x16x32_bf16((a), (b), (c), 0, 0, 0)
; __device__ __forceinline__ void ssd_item(LAS unsigned char* lds, const bf16* proj, const bf16* cxb, bf16* yout, const float* dt_bias, const float* a_log, const float* dskip,
;                                          int gv, int vloc, int hh, int dir) {
;     ...
;         const int qi = 16 * wid + fr;
;         bf16x8 cf[2];
;         cf[0] = ldfrag(CN + qi * LDS_ + 8 * fq); cf[1] = ldfrag(CN + qi * LDS_ + 32 + 8 * fq);
;         const float aci = ACUM[qi];
; #pragma unroll
;         for (int ct = 0; ct < 8; ++ct) {
;             f32x4 a = (f32x4){0.f, 0.f, 0.f, 0.f};
; #pragma unroll
;             for (int ks = 0; ks < 2; ++ks) a = MFMA16(ldfrag(BN + (16 * ct + fr) * LDS_ + 32 * ks + 8 * fq), cf[ks], a);
;             const int j0 = 16 * ct + 4 * fq;
;             const f32x4 acj = *(const LAS f32x4*)(ACUM + j0), dtj = *(const LAS f32x4*)(DT + j0);
;             float wv[4];
; #pragma unroll
;             for (int e = 0; e < 4; ++e) { const int j = j0 + e; const bool ok = dir ? (j >= qi) : (j <= qi); wv[e] = ok ? a[e] * __expf(aci - acj[e]) * dtj[e] : 0.f; }
;             u32x2 w; w.x = pk2(wv[0], wv[1]); w.y = pk2(wv[2], wv[3]);
;             *(LAS u32x2*)(PP + qi * LDL + j0) = w;
;         }
;         {
;             const float ea = __expf(aci);
;             f32x4 Y[4];
; #pragma unroll
;             for (int pt = 0; pt < 4; ++pt) {
;                 f32x4 a = (f32x4){0.f, 0.f, 0.f, 0.f};
; #pragma unroll
;                 for (int ks = 0; ks < 2; ++ks) a = MFMA16(ldfrag(HL + (16 * pt + fr) * LDS_ + 32 * ks + 8 * fq), cf[ks], a);
;                 Y[pt] = a * ea;
.LBB0_545:
	v_add_u32_e32 v41, v78, v107
	s_waitcnt lgkmcnt(0)
	s_barrier
	ds_read_b128 v[36:39], v76 offset:17408
	ds_read_b128 v[32:35], v76 offset:17472
	ds_read_b32 v40, v77
	ds_read_b128 v[144:147], v108
	ds_read_b128 v[148:151], v109
	ds_read_b128 v[152:155], v111
	ds_read_b128 v[44:47], v112
	ds_read_b128 v[156:159], v41 offset:35840
	ds_read_b128 v[160:163], v41 offset:35904
	ds_read_b128 v[164:167], v41 offset:38144
	ds_read_b128 v[228:231], v41 offset:38208
	ds_read_b128 v[232:235], v41 offset:40448
	ds_read_b128 v[236:239], v41 offset:40512
	ds_read_b128 v[240:243], v41 offset:42752
	ds_read_b128 v[244:247], v41 offset:42816
	s_waitcnt lgkmcnt(7)
	v_mfma_f32_16x16x32_bf16 v[196:199], v[156:159], v[36:39], 0
	ds_read_b128 v[156:159], v41 offset:45056
	s_waitcnt lgkmcnt(7)
	v_mfma_f32_16x16x32_bf16 v[196:199], v[160:163], v[32:35], v[196:199]
	ds_read_b128 v[160:163], v41 offset:45120
	s_waitcnt lgkmcnt(7)
	v_mfma_f32_16x16x32_bf16 v[200:203], v[164:167], v[36:39], 0
	ds_read_b128 v[164:167], v41 offset:47360
	s_waitcnt lgkmcnt(7)
	v_mfma_f32_16x16x32_bf16 v[200:203], v[228:231], v[32:35], v[200:203]
	ds_read_b128 v[228:231], v41 offset:47424
	s_waitcnt lgkmcnt(7)
	v_mfma_f32_16x16x32_bf16 v[204:207], v[232:235], v[36:39], 0
	ds_read_b128 v[232:235], v41 offset:49664
	s_waitcnt lgkmcnt(7)
	v_mfma_f32_16x16x32_bf16 v[204:207], v[236:239], v[32:35], v[204:207]
	ds_read_b128 v[236:239], v41 offset:49728
	s_waitcnt lgkmcnt(7)
	v_mfma_f32_16x16x32_bf16 v[208:211], v[240:243], v[36:39], 0
	ds_read_b128 v[240:243], v41 offset:51968
	s_waitcnt lgkmcnt(7)
	v_mfma_f32_16x16x32_bf16 v[208:211], v[244:247], v[32:35], v[208:211]
	ds_read_b128 v[244:247], v41 offset:52032
	s_waitcnt lgkmcnt(7)
	v_mfma_f32_16x16x32_bf16 v[212:215], v[156:159], v[36:39], 0
	s_waitcnt lgkmcnt(6)
	v_mfma_f32_16x16x32_bf16 v[212:215], v[160:163], v[32:35], v[212:215]
	s_waitcnt lgkmcnt(5)
	v_mfma_f32_16x16x32_bf16 v[216:219], v[164:167], v[36:39], 0
	s_waitcnt lgkmcnt(4)
	v_mfma_f32_16x16x32_bf16 v[216:219], v[228:231], v[32:35], v[216:219]
	s_waitcnt lgkmcnt(3)
	v_mfma_f32_16x16x32_bf16 v[220:223], v[232:235], v[36:39], 0
	s_waitcnt lgkmcnt(2)
	v_mfma_f32_16x16x32_bf16 v[220:223], v[236:239], v[32:35], v[220:223]
	s_waitcnt lgkmcnt(1)
	v_mfma_f32_16x16x32_bf16 v[224:227], v[240:243], v[36:39], 0
	s_waitcnt lgkmcnt(0)
	v_mfma_f32_16x16x32_bf16 v[224:227], v[244:247], v[32:35], v[224:227]
	ds_read_b128 v[156:159], v126
	ds_read_b128 v[160:163], v126 offset:64
	ds_read_b128 v[164:167], v126 offset:2304
	ds_read_b128 v[228:231], v126 offset:2368
	ds_read_b128 v[232:235], v126 offset:4608
	ds_read_b128 v[236:239], v126 offset:4672
	ds_read_b128 v[240:243], v126 offset:6912
	ds_read_b128 v[244:247], v126 offset:6976
	v_sub_f32_e32 v42, v40, v144
	v_sub_f32_e32 v43, v40, v145
	v_sub_f32_e32 v248, v40, v146
	v_sub_f32_e32 v249, v40, v147
	v_mul_f32_e32 v42, 0x3fb8aa3b, v42
	v_mul_f32_e32 v43, 0x3fb8aa3b, v43
	v_mul_f32_e32 v248, 0x3fb8aa3b, v248
	v_mul_f32_e32 v249, 0x3fb8aa3b, v249
	v_exp_f32_e32 v42, v42
	v_exp_f32_e32 v43, v43
	v_exp_f32_e32 v248, v248
	v_exp_f32_e32 v249, v249
	v_mul_f32_e32 v196, v196, v42
	v_mul_f32_e32 v197, v197, v43
	v_mul_f32_e32 v198, v198, v248
	v_mul_f32_e32 v199, v199, v249
	v_mul_f32_e32 v196, v148, v196
	v_mul_f32_e32 v197, v149, v197
	v_mul_f32_e32 v198, v150, v198
	v_mul_f32_e32 v199, v151, v199
	v_cndmask_b32_e64 v196, 0, v196, s[62:63]
	v_cndmask_b32_e64 v197, 0, v197, s[64:65]
	v_cndmask_b32_e64 v198, 0, v198, s[66:67]
	v_cndmask_b32_e64 v199, 0, v199, s[68:69]
	v_cvt_pk_bf16_f32 v168, v196, v197
	v_cvt_pk_bf16_f32 v169, v198, v199
	ds_write_b64 v110, v[168:169]
	ds_read_b128 v[144:147], v114
	ds_read_b128 v[148:151], v115
	s_waitcnt lgkmcnt(9)
	v_mfma_f32_16x16x32_bf16 v[196:199], v[156:159], v[36:39], 0
	v_mfma_f32_16x16x32_bf16 v[196:199], v[160:163], v[32:35], v[196:199]
	v_sub_f32_e32 v42, v40, v152
	v_sub_f32_e32 v43, v40, v153
	v_sub_f32_e32 v248, v40, v154
	v_sub_f32_e32 v249, v40, v155
	v_mul_f32_e32 v42, 0x3fb8aa3b, v42
	v_mul_f32_e32 v43, 0x3fb8aa3b, v43
	v_mul_f32_e32 v248, 0x3fb8aa3b, v248
	v_mul_f32_e32 v249, 0x3fb8aa3b, v249
	v_exp_f32_e32 v42, v42
	v_exp_f32_e32 v43, v43
	v_exp_f32_e32 v248, v248
	v_exp_f32_e32 v249, v249
	v_mul_f32_e32 v200, v200, v42
	v_mul_f32_e32 v201, v201, v43
	v_mul_f32_e32 v202, v202, v248
	v_mul_f32_e32 v203, v203, v249
	v_mul_f32_e32 v200, v44, v200
	v_mul_f32_e32 v201, v45, v201
	v_mul_f32_e32 v202, v46, v202
	v_mul_f32_e32 v203, v47, v203
	v_cndmask_b32_e64 v200, 0, v200, s[70:71]
	v_cndmask_b32_e64 v201, 0, v201, s[72:73]
	v_cndmask_b32_e64 v202, 0, v202, s[74:75]
	v_cndmask_b32_e64 v203, 0, v203, s[76:77]
	v_cvt_pk_bf16_f32 v168, v200, v201
	v_cvt_pk_bf16_f32 v169, v202, v203
	ds_write_b64 v110, v[168:169] offset:32
	ds_read_b128 v[152:155], v116
	ds_read_b128 v[44:47], v117
	s_waitcnt lgkmcnt(10)
	v_mfma_f32_16x16x32_bf16 v[200:203], v[164:167], v[36:39], 0
	v_mfma_f32_16x16x32_bf16 v[200:203], v[228:231], v[32:35], v[200:203]
	s_waitcnt lgkmcnt(3)
	v_sub_f32_e32 v42, v40, v144
	v_sub_f32_e32 v43, v40, v145
	v_sub_f32_e32 v248, v40, v146
	v_sub_f32_e32 v249, v40, v147
	v_mul_f32_e32 v42, 0x3fb8aa3b, v42
	v_mul_f32_e32 v43, 0x3fb8aa3b, v43
	v_mul_f32_e32 v248, 0x3fb8aa3b, v248
	v_mul_f32_e32 v249, 0x3fb8aa3b, v249
	v_exp_f32_e32 v42, v42
	v_exp_f32_e32 v43, v43
	v_exp_f32_e32 v248, v248
	v_exp_f32_e32 v249, v249
	v_mul_f32_e32 v204, v204, v42
	v_mul_f32_e32 v205, v205, v43
	v_mul_f32_e32 v206, v206, v248
	v_mul_f32_e32 v207, v207, v249
	v_mul_f32_e32 v204, v148, v204
	v_mul_f32_e32 v205, v149, v205
	v_mul_f32_e32 v206, v150, v206
	v_mul_f32_e32 v207, v151, v207
	v_cndmask_b32_e64 v204, 0, v204, s[78:79]
	v_cndmask_b32_e64 v205, 0, v205, s[80:81]
	v_cndmask_b32_e64 v206, 0, v206, s[82:83]
	v_cndmask_b32_e64 v207, 0, v207, s[84:85]
	v_cvt_pk_bf16_f32 v168, v204, v205
	v_cvt_pk_bf16_f32 v169, v206, v207
	ds_write_b64 v110, v[168:169] offset:64
	ds_read_b128 v[144:147], v118
	ds_read_b128 v[148:151], v119
	v_mfma_f32_16x16x32_bf16 v[204:207], v[232:235], v[36:39], 0
	v_mfma_f32_16x16x32_bf16 v[204:207], v[236:239], v[32:35], v[204:207]
	s_waitcnt lgkmcnt(3)
; #define LAS __attribute__((address_space(3)))
; __device__ __forceinline__ unsigned pk2(float lo, float hi) { return pg8::cvt_pk_bf16(lo, hi); }
; #define MFMA16(a, b, c) __builtin_amdgcn_mfma_f32_16x16x32_bf16((a), (b), (c), 0, 0, 0)
; __device__ __forceinline__ void ssd_item(LAS unsigned char* lds, const bf16* proj, const bf16* cxb, bf16* yout, const float* dt_bias, const float* a_log, const float* dskip,
;                                          int gv, int vloc, int hh, int dir) {
;     ...
;             const int j0 = 16 * ct + 4 * fq;
;             const f32x4 acj = *(const LAS f32x4*)(ACUM + j0), dtj = *(const LAS f32x4*)(DT + j0);
;             float wv[4];
; #pragma unroll
;             for (int e = 0; e < 4; ++e) { const int j = j0 + e; const bool ok = dir ? (j >= qi) : (j <= qi); wv[e] = ok ? a[e] * __expf(aci - acj[e]) * dtj[e] : 0.f; }
;             u32x2 w; w.x = pk2(wv[0], wv[1]); w.y = pk2(wv[2], wv[3]);
;             *(LAS u32x2*)(PP + qi * LDL + j0) = w;
;         }
;     ...
;                 for (int ks = 0; ks < 2; ++ks) a = MFMA16(ldfrag(HL + (16 * pt + fr) * LDS_ + 32 * ks + 8 * fq), cf[ks], a);
	v_sub_f32_e32 v42, v40, v152
	v_sub_f32_e32 v43, v40, v153
	v_sub_f32_e32 v248, v40, v154
	v_sub_f32_e32 v249, v40, v155
	v_mul_f32_e32 v42, 0x3fb8aa3b, v42
	v_mul_f32_e32 v43, 0x3fb8aa3b, v43
	v_mul_f32_e32 v248, 0x3fb8aa3b, v248
	v_mul_f32_e32 v249, 0x3fb8aa3b, v249
	v_exp_f32_e32 v42, v42
	v_exp_f32_e32 v43, v43
	v_exp_f32_e32 v248, v248
	v_exp_f32_e32 v249, v249
	v_mul_f32_e32 v208, v208, v42
	v_mul_f32_e32 v209, v209, v43
	v_mul_f32_e32 v210, v210, v248
	v_mul_f32_e32 v211, v211, v249
	v_mul_f32_e32 v208, v44, v208
	v_mul_f32_e32 v209, v45, v209
	v_mul_f32_e32 v210, v46, v210
	v_mul_f32_e32 v211, v47, v211
	v_cndmask_b32_e64 v208, 0, v208, s[86:87]
	v_cndmask_b32_e64 v209, 0, v209, s[88:89]
	v_cndmask_b32_e64 v210, 0, v210, s[90:91]
	v_cndmask_b32_e64 v211, 0, v211, s[92:93]
	v_cvt_pk_bf16_f32 v168, v208, v209
	v_cvt_pk_bf16_f32 v169, v210, v211
	ds_write_b64 v110, v[168:169] offset:96
	ds_read_b128 v[152:155], v120
	ds_read_b128 v[44:47], v121
	v_mfma_f32_16x16x32_bf16 v[208:211], v[240:243], v[36:39], 0
	v_mfma_f32_16x16x32_bf16 v[208:211], v[244:247], v[32:35], v[208:211]
	ds_read_b128 v[156:159], v127
	ds_read_b128 v[160:163], v127 offset:4352
	ds_read_b128 v[164:167], v127 offset:8704
	ds_read_b128 v[228:231], v127 offset:13056
	ds_read_b128 v[232:235], v127 offset:64
	ds_read_b128 v[236:239], v127 offset:4416
	ds_read_b128 v[240:243], v127 offset:8768
	ds_read_b128 v[244:247], v127 offset:13120
	s_waitcnt lgkmcnt(11)
	v_sub_f32_e32 v42, v40, v144
	v_sub_f32_e32 v43, v40, v145
	v_sub_f32_e32 v248, v40, v146
	v_sub_f32_e32 v249, v40, v147
	v_mul_f32_e32 v42, 0x3fb8aa3b, v42
	v_mul_f32_e32 v43, 0x3fb8aa3b, v43
	v_mul_f32_e32 v248, 0x3fb8aa3b, v248
	v_mul_f32_e32 v249, 0x3fb8aa3b, v249
	v_exp_f32_e32 v42, v42
	v_exp_f32_e32 v43, v43
	v_exp_f32_e32 v248, v248
	v_exp_f32_e32 v249, v249
	v_mul_f32_e32 v212, v212, v42
	v_mul_f32_e32 v213, v213, v43
	v_mul_f32_e32 v214, v214, v248
	v_mul_f32_e32 v215, v215, v249
	v_mul_f32_e32 v212, v148, v212
	v_mul_f32_e32 v213, v149, v213
	v_mul_f32_e32 v214, v150, v214
	v_mul_f32_e32 v215, v151, v215
	v_cndmask_b32_e64 v212, 0, v212, s[94:95]
	v_cndmask_b32_e64 v213, 0, v213, s[96:97]
	v_cndmask_b32_e64 v214, 0, v214, s[4:5]
	v_cndmask_b32_e64 v215, 0, v215, s[6:7]
	v_cvt_pk_bf16_f32 v168, v212, v213
	v_cvt_pk_bf16_f32 v169, v214, v215
	ds_write_b64 v110, v[168:169] offset:128
	ds_read_b128 v[144:147], v122
	ds_read_b128 v[148:151], v123
	s_waitcnt lgkmcnt(11)
	v_sub_f32_e32 v42, v40, v152
	v_sub_f32_e32 v43, v40, v153
	v_sub_f32_e32 v248, v40, v154
	v_sub_f32_e32 v249, v40, v155
	v_mul_f32_e32 v42, 0x3fb8aa3b, v42
	v_mul_f32_e32 v43, 0x3fb8aa3b, v43
	v_mul_f32_e32 v248, 0x3fb8aa3b, v248
	v_mul_f32_e32 v249, 0x3fb8aa3b, v249
	v_exp_f32_e32 v42, v42
	v_exp_f32_e32 v43, v43
	v_exp_f32_e32 v248, v248
	v_exp_f32_e32 v249, v249
	v_mul_f32_e32 v216, v216, v42
	v_mul_f32_e32 v217, v217, v43
	v_mul_f32_e32 v218, v218, v248
	v_mul_f32_e32 v219, v219, v249
	v_mul_f32_e32 v216, v44, v216
	v_mul_f32_e32 v217, v45, v217
	v_mul_f32_e32 v218, v46, v218
	v_mul_f32_e32 v219, v47, v219
	v_cndmask_b32_e64 v216, 0, v216, s[8:9]
	v_cndmask_b32_e64 v217, 0, v217, s[10:11]
	v_cndmask_b32_e64 v218, 0, v218, s[12:13]
	v_cndmask_b32_e64 v219, 0, v219, s[14:15]
	v_cvt_pk_bf16_f32 v168, v216, v217
	v_cvt_pk_bf16_f32 v169, v218, v219
	ds_write_b64 v110, v[168:169] offset:160
	ds_read_b128 v[152:155], v124
	ds_read_b128 v[44:47], v125
	s_waitcnt lgkmcnt(3)
	v_sub_f32_e32 v42, v40, v144
	v_sub_f32_e32 v43, v40, v145
	v_sub_f32_e32 v248, v40, v146
	v_sub_f32_e32 v249, v40, v147
	v_mul_f32_e32 v42, 0x3fb8aa3b, v42
	v_mul_f32_e32 v43, 0x3fb8aa3b, v43
	v_mul_f32_e32 v248, 0x3fb8aa3b, v248
	v_mul_f32_e32 v249, 0x3fb8aa3b, v249
	v_exp_f32_e32 v42, v42
	v_exp_f32_e32 v43, v43
	v_exp_f32_e32 v248, v248
	v_exp_f32_e32 v249, v249
	v_mul_f32_e32 v220, v220, v42
	v_mul_f32_e32 v221, v221, v43
	v_mul_f32_e32 v222, v222, v248
	v_mul_f32_e32 v223, v223, v249
	v_mul_f32_e32 v220, v148, v220
	v_mul_f32_e32 v221, v149, v221
	v_mul_f32_e32 v222, v150, v222
	v_mul_f32_e32 v223, v151, v223
	v_cndmask_b32_e64 v220, 0, v220, s[16:17]
	v_cndmask_b32_e64 v221, 0, v221, s[18:19]
	v_cndmask_b32_e64 v222, 0, v222, s[20:21]
	v_cndmask_b32_e64 v223, 0, v223, s[22:23]
	v_cvt_pk_bf16_f32 v168, v220, v221
	v_cvt_pk_bf16_f32 v169, v222, v223
	ds_write_b64 v110, v[168:169] offset:192
	s_waitcnt lgkmcnt(1)
; #define MFMA16(a, b, c) __builtin_amdgcn_mfma_f32_16x16x32_bf16((a), (b), (c), 0, 0, 0)
; __device__ __forceinline__ void ssd_item(LAS unsigned char* lds, const bf16* proj, const bf16* cxb, bf16* yout, const float* dt_bias, const float* a_log, const float* dskip,
;                                          int gv, int vloc, int hh, int dir) {
;     ...
;         }
;         {
;             const float ea = __expf(aci);
;             f32x4 Y[4];
; #pragma unroll
;             for (int pt = 0; pt < 4; ++pt) {
;                 f32x4 a = (f32x4){0.f, 0.f, 0.f, 0.f};
; #pragma unroll
;                 for (int ks = 0; ks < 2; ++ks) a = MFMA16(ldfrag(HL + (16 * pt + fr) * LDS_ + 32 * ks + 8 * fq), cf[ks], a);
;                 Y[pt] = a * ea;
;             }
; #pragma unroll
;             for (int ks = 0; ks < 4; ++ks) {
;                 const bf16x8 pf = ldfrag(PP + qi * LDL + 32 * ks + 8 * fq);
; #pragma unroll
;                 for (int pt = 0; pt < 4; ++pt) Y[pt] = MFMA16(ldfrag(XST + (16 * pt + fr) * LDL + 32 * ks + 8 * fq), pf, Y[pt]);
;             }
;             bf16* yo = yout + (size_t)(lrow0 + qi) * YLD + 512 + 64 * hh + 4 * fq;
; #pragma unroll
;             for (int pt = 0; pt < 4; ++pt) {
;                 if (dir == 0) {
; #pragma unroll
;                     for (int e = 0; e < 4; ++e) Y[pt][e] += dsk * bf2f(XST[(16 * pt + 4 * fq + e) * LDL + qi]);
	v_sub_f32_e32 v42, v40, v152
	v_sub_f32_e32 v43, v40, v153
	v_sub_f32_e32 v248, v40, v154
	v_sub_f32_e32 v249, v40, v155
	v_mul_f32_e32 v42, 0x3fb8aa3b, v42
	v_mul_f32_e32 v43, 0x3fb8aa3b, v43
	v_mul_f32_e32 v248, 0x3fb8aa3b, v248
	v_mul_f32_e32 v249, 0x3fb8aa3b, v249
	v_exp_f32_e32 v42, v42
	v_exp_f32_e32 v43, v43
	v_exp_f32_e32 v248, v248
	v_exp_f32_e32 v249, v249
	v_mul_f32_e32 v224, v224, v42
	v_mul_f32_e32 v225, v225, v43
	v_mul_f32_e32 v226, v226, v248
	v_mul_f32_e32 v227, v227, v249
	v_mul_f32_e32 v224, v44, v224
	v_mul_f32_e32 v225, v45, v225
	v_mul_f32_e32 v226, v46, v226
	v_mul_f32_e32 v227, v47, v227
	v_cndmask_b32_e64 v224, 0, v224, s[24:25]
	v_cndmask_b32_e64 v225, 0, v225, s[26:27]
	v_cndmask_b32_e64 v226, 0, v226, s[28:29]
	v_cndmask_b32_e64 v227, 0, v227, s[30:31]
	v_cvt_pk_bf16_f32 v168, v224, v225
	v_cvt_pk_bf16_f32 v169, v226, v227
	ds_write_b64 v110, v[168:169] offset:224
	v_mul_f32_e32 v43, 0x3fb8aa3b, v40
	v_exp_f32_e32 v43, v43
	ds_read_b128 v[212:215], v79
	ds_read_b128 v[216:219], v79 offset:64
	ds_read_b128 v[220:223], v79 offset:128
	ds_read_b128 v[224:227], v79 offset:192
	v_mul_f32_e32 v196, v43, v196
	v_mul_f32_e32 v197, v43, v197
	v_mul_f32_e32 v198, v43, v198
	v_mul_f32_e32 v199, v43, v199
	v_mul_f32_e32 v200, v43, v200
	v_mul_f32_e32 v201, v43, v201
	v_mul_f32_e32 v202, v43, v202
	v_mul_f32_e32 v203, v43, v203
	v_mul_f32_e32 v204, v43, v204
	v_mul_f32_e32 v205, v43, v205
	v_mul_f32_e32 v206, v43, v206
	v_mul_f32_e32 v207, v43, v207
	v_mul_f32_e32 v208, v43, v208
	v_mul_f32_e32 v209, v43, v209
	v_mul_f32_e32 v210, v43, v210
	v_mul_f32_e32 v211, v43, v211
	s_waitcnt lgkmcnt(0)
	v_mfma_f32_16x16x32_bf16 v[196:199], v[156:159], v[212:215], v[196:199]
	ds_read_b128 v[156:159], v127 offset:128
	v_mfma_f32_16x16x32_bf16 v[200:203], v[160:163], v[212:215], v[200:203]
	ds_read_b128 v[160:163], v127 offset:4480
	v_mfma_f32_16x16x32_bf16 v[204:207], v[164:167], v[212:215], v[204:207]
	ds_read_b128 v[164:167], v127 offset:8832
	v_mfma_f32_16x16x32_bf16 v[208:211], v[228:231], v[212:215], v[208:211]
	ds_read_b128 v[228:231], v127 offset:13184
	v_mfma_f32_16x16x32_bf16 v[196:199], v[232:235], v[216:219], v[196:199]
	ds_read_b128 v[232:235], v127 offset:192
	v_mfma_f32_16x16x32_bf16 v[200:203], v[236:239], v[216:219], v[200:203]
	ds_read_b128 v[236:239], v127 offset:4544
	v_mfma_f32_16x16x32_bf16 v[204:207], v[240:243], v[216:219], v[204:207]
	ds_read_b128 v[240:243], v127 offset:8896
	v_mfma_f32_16x16x32_bf16 v[208:211], v[244:247], v[216:219], v[208:211]
	ds_read_b128 v[244:247], v127 offset:13248
	s_waitcnt lgkmcnt(7)
	v_mfma_f32_16x16x32_bf16 v[196:199], v[156:159], v[220:223], v[196:199]
	s_waitcnt lgkmcnt(6)
	v_mfma_f32_16x16x32_bf16 v[200:203], v[160:163], v[220:223], v[200:203]
	s_waitcnt lgkmcnt(5)
	v_mfma_f32_16x16x32_bf16 v[204:207], v[164:167], v[220:223], v[204:207]
	s_waitcnt lgkmcnt(4)
	v_mfma_f32_16x16x32_bf16 v[208:211], v[228:231], v[220:223], v[208:211]
	s_waitcnt lgkmcnt(3)
	v_mfma_f32_16x16x32_bf16 v[196:199], v[232:235], v[224:227], v[196:199]
	s_waitcnt lgkmcnt(2)
	v_mfma_f32_16x16x32_bf16 v[200:203], v[236:239], v[224:227], v[200:203]
	s_waitcnt lgkmcnt(1)
	v_mfma_f32_16x16x32_bf16 v[204:207], v[240:243], v[224:227], v[204:207]
	s_waitcnt lgkmcnt(0)
	v_mfma_f32_16x16x32_bf16 v[208:211], v[244:247], v[224:227], v[208:211]
	s_andn2_b64 vcc, exec, s[38:39]
	s_cbranch_vccnz .Lssd_nodskip
	ds_read_u16 v144, v135
	ds_read_u16 v145, v135 offset:272
	ds_read_u16 v146, v135 offset:544
	ds_read_u16 v147, v135 offset:816
	ds_read_u16 v148, v136
	ds_read_u16 v149, v135 offset:4624
	ds_read_u16 v150, v135 offset:4896
	ds_read_u16 v151, v135 offset:5168
	ds_read_u16 v152, v136 offset:4352
	ds_read_u16 v153, v135 offset:8976
	ds_read_u16 v154, v135 offset:9248
	ds_read_u16 v155, v135 offset:9520
	s_waitcnt lgkmcnt(8)
	ds_read_u16 v44, v136 offset:8704
	ds_read_u16 v45, v135 offset:13328
	ds_read_u16 v46, v135 offset:13600
	ds_read_u16 v47, v135 offset:13872
	s_waitcnt lgkmcnt(0)
	v_lshlrev_b32_e32 v144, 16, v144
	v_lshlrev_b32_e32 v145, 16, v145
	v_lshlrev_b32_e32 v146, 16, v146
	v_lshlrev_b32_e32 v147, 16, v147
	v_lshlrev_b32_e32 v148, 16, v148
	v_lshlrev_b32_e32 v149, 16, v149
	v_lshlrev_b32_e32 v150, 16, v150
	v_lshlrev_b32_e32 v151, 16, v151
	v_lshlrev_b32_e32 v152, 16, v152
	v_lshlrev_b32_e32 v153, 16, v153
	v_lshlrev_b32_e32 v154, 16, v154
	v_lshlrev_b32_e32 v155, 16, v155
	v_lshlrev_b32_e32 v44, 16, v44
	v_lshlrev_b32_e32 v45, 16, v45
	v_lshlrev_b32_e32 v46, 16, v46
	v_lshlrev_b32_e32 v47, 16, v47
	v_pk_fma_f32 v[196:197], v[48:49], v[144:145], v[196:197]
	v_pk_fma_f32 v[198:199], v[48:49], v[146:147], v[198:199]
	v_pk_fma_f32 v[200:201], v[48:49], v[148:149], v[200:201]
	v_pk_fma_f32 v[202:203], v[48:49], v[150:151], v[202:203]
	v_pk_fma_f32 v[204:205], v[48:49], v[152:153], v[204:205]
	v_pk_fma_f32 v[206:207], v[48:49], v[154:155], v[206:207]
	v_pk_fma_f32 v[208:209], v[48:49], v[44:45], v[208:209]
	v_pk_fma_f32 v[210:211], v[48:49], v[46:47], v[210:211]

; __device__ __forceinline__ unsigned pk2(float lo, float hi) { return pg8::cvt_pk_bf16(lo, hi); }
;     __device__ __forceinline__ void operator()(const pg8::f32x4 (&acc)[2][2][4][2], const pg8::Unit& u, int wr, int wc, int fr, int fq) const {
;         const int row0 = row_off + u.pm * 256 + wr * 64 + fr, col0 = u.pn * 256 + wc * 32 + 8 * fq;
; #pragma unroll
;         for (int ai = 0; ai < 2; ++ai)
; #pragma unroll
;             for (int m = 0; m < 4; ++m) {
;                 const size_t row = (size_t)(row0 + ai * 128 + m * 16);
;                 float s = 0.f;
; #pragma unroll
;                 for (int bj = 0; bj < 2; ++bj) {
;                     float* xp = X + row * DM + col0 + bj * 128;
;                     pg8::f32x4 x0 = *(const pg8::f32x4*)xp, x1 = *(const pg8::f32x4*)(xp + 4);
;                     x0 += acc[ai][bj][m][0] * coef; x1 += acc[ai][bj][m][1] * coef;
;                     *(pg8::f32x4*)xp = x0; *(pg8::f32x4*)(xp + 4) = x1;
;                     s += (x0[0] * x0[0] + x0[1] * x0[1]) + (x0[2] * x0[2] + x0[3] * x0[3]) + (x1[0] * x1[0] + x1[1] * x1[1]) + (x1[2] * x1[2] + x1[3] * x1[3]);
;                     u32x4 w; w.x = pk2(x0[0], x0[1]); w.y = pk2(x0[2], x0[3]); w.z = pk2(x1[0], x1[1]); w.w = pk2(x1[2], x1[3]);
;                     *(u32x4*)(XB + row * DM + col0 + bj * 128) = w;
;                 }
;                 s += __shfl_xor(s, 16); s += __shfl_xor(s, 32);
.LBB0_798:
	v_readlane_b32 s52, v251, 5
	v_readlane_b32 s53, v251, 6
	v_readlane_b32 s28, v251, 11
	v_readlane_b32 s29, v251, 12
	v_readlane_b32 s30, v251, 13
	v_readlane_b32 s31, v251, 14
	v_lshl_add_u32 v144, s50, 8, v147
	v_lshl_or_b32 v142, s49, 8, v146
	v_lshlrev_b32_e32 v149, 12, v144
	v_lshl_add_u32 v149, v142, 2, v149
	s_lshl_b32 s50, s49, 4
	s_lshl_b32 s51, s43, 2
	s_add_i32 s50, s50, s51
	v_and_b32_e32 v245, 64, v175
	v_xor_b32_e32 v244, 16, v175
	v_add_u32_e32 v245, 64, v245
	v_cmp_lt_i32_e32 vcc, v244, v245
	s_nop 1
	v_cndmask_b32_e32 v244, v175, v244, vcc
	v_lshlrev_b32_e32 v143, 2, v244
	v_xor_b32_e32 v244, 32, v175
	v_cmp_lt_i32_e32 vcc, v244, v245
	s_nop 1
	v_cndmask_b32_e32 v244, v175, v244, vcc
	v_lshlrev_b32_e32 v145, 2, v244
	v_mov_b32_e32 v142, v149
	global_load_dwordx4 v[200:203], v142, s[52:53]
	global_load_dwordx4 v[196:199], v142, s[52:53] offset:16
	global_load_dwordx4 v[208:211], v142, s[52:53] offset:512
	global_load_dwordx4 v[204:207], v142, s[52:53] offset:528
	v_add_u32_e32 v142, 0x10000, v149
	global_load_dwordx4 v[216:219], v142, s[52:53]
	global_load_dwordx4 v[212:215], v142, s[52:53] offset:16
	global_load_dwordx4 v[224:227], v142, s[52:53] offset:512
	global_load_dwordx4 v[220:223], v142, s[52:53] offset:528
	v_add_u32_e32 v142, 0x20000, v149
	global_load_dwordx4 v[232:235], v142, s[52:53]
	global_load_dwordx4 v[228:231], v142, s[52:53] offset:16
	global_load_dwordx4 v[240:243], v142, s[52:53] offset:512
	global_load_dwordx4 v[236:239], v142, s[52:53] offset:528
	v_add_u32_e32 v142, 0x30000, v149
	global_load_dwordx4 v[154:157], v142, s[52:53]
	global_load_dwordx4 v[150:153], v142, s[52:53] offset:16
	global_load_dwordx4 v[162:165], v142, s[52:53] offset:512
	global_load_dwordx4 v[158:161], v142, s[52:53] offset:528
	s_waitcnt vmcnt(12)
	v_mov_b32_e32 v142, v149
	v_lshrrev_b32_e32 v144, 1, v142
	v_pk_fma_f32 v[124:125], s[10:11], v[124:125], v[200:201]
	v_pk_fma_f32 v[126:127], s[24:25], v[126:127], v[202:203]
	v_pk_fma_f32 v[120:121], s[10:11], v[120:121], v[196:197]
	v_pk_fma_f32 v[122:123], s[24:25], v[122:123], v[198:199]
	v_pk_fma_f32 v[116:117], s[10:11], v[116:117], v[208:209]
	v_pk_fma_f32 v[118:119], s[24:25], v[118:119], v[210:211]
	v_pk_fma_f32 v[112:113], s[10:11], v[112:113], v[204:205]
	v_pk_fma_f32 v[114:115], s[24:25], v[114:115], v[206:207]
	v_add_u32_e32 v245, 0x80000, v149
	global_load_dwordx4 v[200:203], v245, s[52:53]
	global_load_dwordx4 v[196:199], v245, s[52:53] offset:16
	global_load_dwordx4 v[208:211], v245, s[52:53] offset:512
	global_load_dwordx4 v[204:207], v245, s[52:53] offset:528
	global_store_dwordx4 v142, v[124:127], s[52:53]
	global_store_dwordx4 v142, v[120:123], s[52:53] offset:16
	v_mul_f32_e32 v166, v125, v125
	v_fmac_f32_e32 v166, v124, v124
	v_mul_f32_e32 v245, v127, v127
	v_fmac_f32_e32 v245, v126, v126
	v_add_f32_e32 v166, v166, v245
	v_mul_f32_e32 v245, v121, v121
	v_fmac_f32_e32 v245, v120, v120
	v_add_f32_e32 v166, v245, v166
	v_mul_f32_e32 v245, v123, v123
	v_fmac_f32_e32 v245, v122, v122
	v_add_f32_e32 v166, v245, v166
	v_cvt_pk_bf16_f32 v124, v124, v125
	v_cvt_pk_bf16_f32 v125, v126, v127
	v_cvt_pk_bf16_f32 v126, v120, v121
	v_cvt_pk_bf16_f32 v127, v122, v123
	global_store_dwordx4 v144, v[124:127], s[28:29]
	global_store_dwordx4 v142, v[116:119], s[52:53] offset:512
	global_store_dwordx4 v142, v[112:115], s[52:53] offset:528
	v_mul_f32_e32 v244, v117, v117
	v_fmac_f32_e32 v244, v116, v116
	v_mul_f32_e32 v245, v119, v119
	v_fmac_f32_e32 v245, v118, v118
	v_add_f32_e32 v244, v244, v245
	v_mul_f32_e32 v245, v113, v113
	v_fmac_f32_e32 v245, v112, v112
	v_add_f32_e32 v244, v245, v244
	v_mul_f32_e32 v245, v115, v115
	v_fmac_f32_e32 v245, v114, v114
	v_add_f32_e32 v244, v245, v244
	v_add_f32_e32 v166, v166, v244
	v_cvt_pk_bf16_f32 v116, v116, v117
	v_cvt_pk_bf16_f32 v117, v118, v119
	v_cvt_pk_bf16_f32 v118, v112, v113
	v_cvt_pk_bf16_f32 v119, v114, v115
	global_store_dwordx4 v144, v[116:119], s[28:29] offset:256
	s_waitcnt vmcnt(18)
	v_add_u32_e32 v142, 0x10000, v149
	v_lshrrev_b32_e32 v144, 1, v142
	v_pk_fma_f32 v[108:109], s[10:11], v[108:109], v[216:217]
	v_pk_fma_f32 v[110:111], s[24:25], v[110:111], v[218:219]
	v_pk_fma_f32 v[104:105], s[10:11], v[104:105], v[212:213]
	v_pk_fma_f32 v[106:107], s[24:25], v[106:107], v[214:215]
	v_pk_fma_f32 v[100:101], s[10:11], v[100:101], v[224:225]
	v_pk_fma_f32 v[102:103], s[24:25], v[102:103], v[226:227]
	v_pk_fma_f32 v[96:97], s[10:11], v[96:97], v[220:221]
	v_pk_fma_f32 v[98:99], s[24:25], v[98:99], v[222:223]
	v_add_u32_e32 v245, 0x90000, v149
	global_load_dwordx4 v[216:219], v245, s[52:53]
	global_load_dwordx4 v[212:215], v245, s[52:53] offset:16
	global_load_dwordx4 v[224:227], v245, s[52:53] offset:512
	global_load_dwordx4 v[220:223], v245, s[52:53] offset:528
	global_store_dwordx4 v142, v[108:111], s[52:53]
	global_store_dwordx4 v142, v[104:107], s[52:53] offset:16
	v_mul_f32_e32 v167, v109, v109
	v_fmac_f32_e32 v167, v108, v108
	v_mul_f32_e32 v245, v111, v111
	v_fmac_f32_e32 v245, v110, v110
	v_add_f32_e32 v167, v167, v245
	v_mul_f32_e32 v245, v105, v105
	v_fmac_f32_e32 v245, v104, v104
	v_add_f32_e32 v167, v245, v167
	v_mul_f32_e32 v245, v107, v107
	v_fmac_f32_e32 v245, v106, v106
	v_add_f32_e32 v167, v245, v167
	v_cvt_pk_bf16_f32 v108, v108, v109
	v_cvt_pk_bf16_f32 v109, v110, v111
	v_cvt_pk_bf16_f32 v110, v104, v105
	v_cvt_pk_bf16_f32 v111, v106, v107
	global_store_dwordx4 v144, v[108:111], s[28:29]
	global_store_dwordx4 v142, v[100:103], s[52:53] offset:512
	global_store_dwordx4 v142, v[96:99], s[52:53] offset:528
	v_mul_f32_e32 v244, v101, v101
	v_fmac_f32_e32 v244, v100, v100
	v_mul_f32_e32 v245, v103, v103
	v_fmac_f32_e32 v245, v102, v102
	v_add_f32_e32 v244, v244, v245
	v_mul_f32_e32 v245, v97, v97
	v_fmac_f32_e32 v245, v96, v96
	v_add_f32_e32 v244, v245, v244
	v_mul_f32_e32 v245, v99, v99
	v_fmac_f32_e32 v245, v98, v98
	v_add_f32_e32 v244, v245, v244
	v_add_f32_e32 v167, v167, v244
	v_cvt_pk_bf16_f32 v100, v100, v101
	v_cvt_pk_bf16_f32 v101, v102, v103
	v_cvt_pk_bf16_f32 v102, v96, v97
	v_cvt_pk_bf16_f32 v103, v98, v99
	global_store_dwordx4 v144, v[100:103], s[28:29] offset:256
	s_waitcnt vmcnt(24)
; __device__ __forceinline__ unsigned pk2(float lo, float hi) { return pg8::cvt_pk_bf16(lo, hi); }
;     __device__ __forceinline__ void operator()(const pg8::f32x4 (&acc)[2][2][4][2], const pg8::Unit& u, int wr, int wc, int fr, int fq) const {
;         const int row0 = row_off + u.pm * 256 + wr * 64 + fr, col0 = u.pn * 256 + wc * 32 + 8 * fq;
; #pragma unroll
;         for (int ai = 0; ai < 2; ++ai)
; #pragma unroll
;             for (int m = 0; m < 4; ++m) {
;                 const size_t row = (size_t)(row0 + ai * 128 + m * 16);
;                 float s = 0.f;
; #pragma unroll
;                 for (int bj = 0; bj < 2; ++bj) {
;                     float* xp = X + row * DM + col0 + bj * 128;
;                     pg8::f32x4 x0 = *(const pg8::f32x4*)xp, x1 = *(const pg8::f32x4*)(xp + 4);
;                     x0 += acc[ai][bj][m][0] * coef; x1 += acc[ai][bj][m][1] * coef;
;                     *(pg8::f32x4*)xp = x0; *(pg8::f32x4*)(xp + 4) = x1;
;                     s += (x0[0] * x0[0] + x0[1] * x0[1]) + (x0[2] * x0[2] + x0[3] * x0[3]) + (x1[0] * x1[0] + x1[1] * x1[1]) + (x1[2] * x1[2] + x1[3] * x1[3]);
;                     u32x4 w; w.x = pk2(x0[0], x0[1]); w.y = pk2(x0[2], x0[3]); w.z = pk2(x1[0], x1[1]); w.w = pk2(x1[2], x1[3]);
;                     *(u32x4*)(XB + row * DM + col0 + bj * 128) = w;
;                 }
;                 s += __shfl_xor(s, 16); s += __shfl_xor(s, 32);
	v_add_u32_e32 v142, 0x20000, v149
	v_lshrrev_b32_e32 v144, 1, v142
	v_pk_fma_f32 v[92:93], s[10:11], v[92:93], v[232:233]
	v_pk_fma_f32 v[94:95], s[24:25], v[94:95], v[234:235]
	v_pk_fma_f32 v[88:89], s[10:11], v[88:89], v[228:229]
	v_pk_fma_f32 v[90:91], s[24:25], v[90:91], v[230:231]
	v_pk_fma_f32 v[84:85], s[10:11], v[84:85], v[240:241]
	v_pk_fma_f32 v[86:87], s[24:25], v[86:87], v[242:243]
	v_pk_fma_f32 v[80:81], s[10:11], v[80:81], v[236:237]
	v_pk_fma_f32 v[82:83], s[24:25], v[82:83], v[238:239]
	v_add_u32_e32 v245, 0xa0000, v149
	global_load_dwordx4 v[232:235], v245, s[52:53]
	global_load_dwordx4 v[228:231], v245, s[52:53] offset:16
	global_load_dwordx4 v[240:243], v245, s[52:53] offset:512
	global_load_dwordx4 v[236:239], v245, s[52:53] offset:528
	global_store_dwordx4 v142, v[92:95], s[52:53]
	global_store_dwordx4 v142, v[88:91], s[52:53] offset:16
	v_mul_f32_e32 v168, v93, v93
	v_fmac_f32_e32 v168, v92, v92
	v_mul_f32_e32 v245, v95, v95
	v_fmac_f32_e32 v245, v94, v94
	v_add_f32_e32 v168, v168, v245
	v_mul_f32_e32 v245, v89, v89
	v_fmac_f32_e32 v245, v88, v88
	v_add_f32_e32 v168, v245, v168
	v_mul_f32_e32 v245, v91, v91
	v_fmac_f32_e32 v245, v90, v90
	v_add_f32_e32 v168, v245, v168
	v_cvt_pk_bf16_f32 v92, v92, v93
	v_cvt_pk_bf16_f32 v93, v94, v95
	v_cvt_pk_bf16_f32 v94, v88, v89
	v_cvt_pk_bf16_f32 v95, v90, v91
	global_store_dwordx4 v144, v[92:95], s[28:29]
	global_store_dwordx4 v142, v[84:87], s[52:53] offset:512
	global_store_dwordx4 v142, v[80:83], s[52:53] offset:528
	v_mul_f32_e32 v244, v85, v85
	v_fmac_f32_e32 v244, v84, v84
	v_mul_f32_e32 v245, v87, v87
	v_fmac_f32_e32 v245, v86, v86
	v_add_f32_e32 v244, v244, v245
	v_mul_f32_e32 v245, v81, v81
	v_fmac_f32_e32 v245, v80, v80
	v_add_f32_e32 v244, v245, v244
	v_mul_f32_e32 v245, v83, v83
	v_fmac_f32_e32 v245, v82, v82
	v_add_f32_e32 v244, v245, v244
	v_add_f32_e32 v168, v168, v244
	v_cvt_pk_bf16_f32 v84, v84, v85
	v_cvt_pk_bf16_f32 v85, v86, v87
	v_cvt_pk_bf16_f32 v86, v80, v81
	v_cvt_pk_bf16_f32 v87, v82, v83
	global_store_dwordx4 v144, v[84:87], s[28:29] offset:256
	s_waitcnt vmcnt(30)
	v_add_u32_e32 v142, 0x30000, v149
	v_lshrrev_b32_e32 v144, 1, v142
	v_pk_fma_f32 v[76:77], s[10:11], v[76:77], v[154:155]
	v_pk_fma_f32 v[78:79], s[24:25], v[78:79], v[156:157]
	v_pk_fma_f32 v[72:73], s[10:11], v[72:73], v[150:151]
	v_pk_fma_f32 v[74:75], s[24:25], v[74:75], v[152:153]
	v_pk_fma_f32 v[68:69], s[10:11], v[68:69], v[162:163]
	v_pk_fma_f32 v[70:71], s[24:25], v[70:71], v[164:165]
	v_pk_fma_f32 v[64:65], s[10:11], v[64:65], v[158:159]
	v_pk_fma_f32 v[66:67], s[24:25], v[66:67], v[160:161]
	v_add_u32_e32 v245, 0xb0000, v149
	global_load_dwordx4 v[154:157], v245, s[52:53]
	global_load_dwordx4 v[150:153], v245, s[52:53] offset:16
	global_load_dwordx4 v[162:165], v245, s[52:53] offset:512
	global_load_dwordx4 v[158:161], v245, s[52:53] offset:528
	global_store_dwordx4 v142, v[76:79], s[52:53]
	global_store_dwordx4 v142, v[72:75], s[52:53] offset:16
	v_mul_f32_e32 v169, v77, v77
	v_fmac_f32_e32 v169, v76, v76
	v_mul_f32_e32 v245, v79, v79
	v_fmac_f32_e32 v245, v78, v78
	v_add_f32_e32 v169, v169, v245
	v_mul_f32_e32 v245, v73, v73
	v_fmac_f32_e32 v245, v72, v72
	v_add_f32_e32 v169, v245, v169
	v_mul_f32_e32 v245, v75, v75
	v_fmac_f32_e32 v245, v74, v74
	v_add_f32_e32 v169, v245, v169
	v_cvt_pk_bf16_f32 v76, v76, v77
	v_cvt_pk_bf16_f32 v77, v78, v79
	v_cvt_pk_bf16_f32 v78, v72, v73
	v_cvt_pk_bf16_f32 v79, v74, v75
	global_store_dwordx4 v144, v[76:79], s[28:29]
	global_store_dwordx4 v142, v[68:71], s[52:53] offset:512
	global_store_dwordx4 v142, v[64:67], s[52:53] offset:528
	v_mul_f32_e32 v244, v69, v69
	v_fmac_f32_e32 v244, v68, v68
	v_mul_f32_e32 v245, v71, v71
	v_fmac_f32_e32 v245, v70, v70
	v_add_f32_e32 v244, v244, v245
	v_mul_f32_e32 v245, v65, v65
	v_fmac_f32_e32 v245, v64, v64
	v_add_f32_e32 v244, v245, v244
	v_mul_f32_e32 v245, v67, v67
	v_fmac_f32_e32 v245, v66, v66
	v_add_f32_e32 v244, v245, v244
	v_add_f32_e32 v169, v169, v244
	v_cvt_pk_bf16_f32 v68, v68, v69
	v_cvt_pk_bf16_f32 v69, v70, v71
	v_cvt_pk_bf16_f32 v70, v64, v65
	v_cvt_pk_bf16_f32 v71, v66, v67
	global_store_dwordx4 v144, v[68:71], s[28:29] offset:256
	s_waitcnt vmcnt(36)
	v_add_u32_e32 v142, 0x80000, v149
	v_lshrrev_b32_e32 v144, 1, v142
	v_pk_fma_f32 v[60:61], s[10:11], v[60:61], v[200:201]
	v_pk_fma_f32 v[62:63], s[24:25], v[62:63], v[202:203]
	v_pk_fma_f32 v[56:57], s[10:11], v[56:57], v[196:197]
	v_pk_fma_f32 v[58:59], s[24:25], v[58:59], v[198:199]
	v_pk_fma_f32 v[52:53], s[10:11], v[52:53], v[208:209]
	v_pk_fma_f32 v[54:55], s[24:25], v[54:55], v[210:211]
	v_pk_fma_f32 v[48:49], s[10:11], v[48:49], v[204:205]
	v_pk_fma_f32 v[50:51], s[24:25], v[50:51], v[206:207]
	global_store_dwordx4 v142, v[60:63], s[52:53]
	global_store_dwordx4 v142, v[56:59], s[52:53] offset:16
	v_mul_f32_e32 v176, v61, v61
	v_fmac_f32_e32 v176, v60, v60
	v_mul_f32_e32 v245, v63, v63
	v_fmac_f32_e32 v245, v62, v62
	v_add_f32_e32 v176, v176, v245
	v_mul_f32_e32 v245, v57, v57
	v_fmac_f32_e32 v245, v56, v56
	v_add_f32_e32 v176, v245, v176
	v_mul_f32_e32 v245, v59, v59
	v_fmac_f32_e32 v245, v58, v58
	v_add_f32_e32 v176, v245, v176
	v_cvt_pk_bf16_f32 v60, v60, v61
	v_cvt_pk_bf16_f32 v61, v62, v63
	v_cvt_pk_bf16_f32 v62, v56, v57
	v_cvt_pk_bf16_f32 v63, v58, v59
	global_store_dwordx4 v144, v[60:63], s[28:29]
	global_store_dwordx4 v142, v[52:55], s[52:53] offset:512
	global_store_dwordx4 v142, v[48:51], s[52:53] offset:528
	v_mul_f32_e32 v244, v53, v53
	v_fmac_f32_e32 v244, v52, v52
	v_mul_f32_e32 v245, v55, v55
	v_fmac_f32_e32 v245, v54, v54
	v_add_f32_e32 v244, v244, v245
	v_mul_f32_e32 v245, v49, v49
	v_fmac_f32_e32 v245, v48, v48
	v_add_f32_e32 v244, v245, v244
	v_mul_f32_e32 v245, v51, v51
	v_fmac_f32_e32 v245, v50, v50
	v_add_f32_e32 v244, v245, v244
	v_add_f32_e32 v176, v176, v244
	v_cvt_pk_bf16_f32 v52, v52, v53
	v_cvt_pk_bf16_f32 v53, v54, v55
	v_cvt_pk_bf16_f32 v54, v48, v49
	v_cvt_pk_bf16_f32 v55, v50, v51
	global_store_dwordx4 v144, v[52:55], s[28:29] offset:256
	s_waitcnt vmcnt(32)
; __device__ __forceinline__ unsigned pk2(float lo, float hi) { return pg8::cvt_pk_bf16(lo, hi); }
;     __device__ __forceinline__ void operator()(const pg8::f32x4 (&acc)[2][2][4][2], const pg8::Unit& u, int wr, int wc, int fr, int fq) const {
;         const int row0 = row_off + u.pm * 256 + wr * 64 + fr, col0 = u.pn * 256 + wc * 32 + 8 * fq;
; #pragma unroll
;         for (int ai = 0; ai < 2; ++ai)
; #pragma unroll
;             for (int m = 0; m < 4; ++m) {
;                 const size_t row = (size_t)(row0 + ai * 128 + m * 16);
;                 float s = 0.f;
; #pragma unroll
;                 for (int bj = 0; bj < 2; ++bj) {
;                     float* xp = X + row * DM + col0 + bj * 128;
;                     pg8::f32x4 x0 = *(const pg8::f32x4*)xp, x1 = *(const pg8::f32x4*)(xp + 4);
;                     x0 += acc[ai][bj][m][0] * coef; x1 += acc[ai][bj][m][1] * coef;
;                     *(pg8::f32x4*)xp = x0; *(pg8::f32x4*)(xp + 4) = x1;
;                     s += (x0[0] * x0[0] + x0[1] * x0[1]) + (x0[2] * x0[2] + x0[3] * x0[3]) + (x1[0] * x1[0] + x1[1] * x1[1]) + (x1[2] * x1[2] + x1[3] * x1[3]);
;                     u32x4 w; w.x = pk2(x0[0], x0[1]); w.y = pk2(x0[2], x0[3]); w.z = pk2(x1[0], x1[1]); w.w = pk2(x1[2], x1[3]);
;                     *(u32x4*)(XB + row * DM + col0 + bj * 128) = w;
;                 }
;                 s += __shfl_xor(s, 16); s += __shfl_xor(s, 32);
	v_add_u32_e32 v142, 0x90000, v149
	v_lshrrev_b32_e32 v144, 1, v142
	v_pk_fma_f32 v[44:45], s[10:11], v[44:45], v[216:217]
	v_pk_fma_f32 v[46:47], s[24:25], v[46:47], v[218:219]
	v_pk_fma_f32 v[40:41], s[10:11], v[40:41], v[212:213]
	v_pk_fma_f32 v[42:43], s[24:25], v[42:43], v[214:215]
	v_pk_fma_f32 v[36:37], s[10:11], v[36:37], v[224:225]
	v_pk_fma_f32 v[38:39], s[24:25], v[38:39], v[226:227]
	v_pk_fma_f32 v[32:33], s[10:11], v[32:33], v[220:221]
	v_pk_fma_f32 v[34:35], s[24:25], v[34:35], v[222:223]
	global_store_dwordx4 v142, v[44:47], s[52:53]
	global_store_dwordx4 v142, v[40:43], s[52:53] offset:16
	v_mul_f32_e32 v177, v45, v45
	v_fmac_f32_e32 v177, v44, v44
	v_mul_f32_e32 v245, v47, v47
	v_fmac_f32_e32 v245, v46, v46
	v_add_f32_e32 v177, v177, v245
	v_mul_f32_e32 v245, v41, v41
	v_fmac_f32_e32 v245, v40, v40
	v_add_f32_e32 v177, v245, v177
	v_mul_f32_e32 v245, v43, v43
	v_fmac_f32_e32 v245, v42, v42
	v_add_f32_e32 v177, v245, v177
	v_cvt_pk_bf16_f32 v44, v44, v45
	v_cvt_pk_bf16_f32 v45, v46, v47
	v_cvt_pk_bf16_f32 v46, v40, v41
	v_cvt_pk_bf16_f32 v47, v42, v43
	global_store_dwordx4 v144, v[44:47], s[28:29]
	global_store_dwordx4 v142, v[36:39], s[52:53] offset:512
	global_store_dwordx4 v142, v[32:35], s[52:53] offset:528
	v_mul_f32_e32 v244, v37, v37
	v_fmac_f32_e32 v244, v36, v36
	v_mul_f32_e32 v245, v39, v39
	v_fmac_f32_e32 v245, v38, v38
	v_add_f32_e32 v244, v244, v245
	v_mul_f32_e32 v245, v33, v33
	v_fmac_f32_e32 v245, v32, v32
	v_add_f32_e32 v244, v245, v244
	v_mul_f32_e32 v245, v35, v35
	v_fmac_f32_e32 v245, v34, v34
	v_add_f32_e32 v244, v245, v244
	v_add_f32_e32 v177, v177, v244
	v_cvt_pk_bf16_f32 v36, v36, v37
	v_cvt_pk_bf16_f32 v37, v38, v39
	v_cvt_pk_bf16_f32 v38, v32, v33
	v_cvt_pk_bf16_f32 v39, v34, v35
	global_store_dwordx4 v144, v[36:39], s[28:29] offset:256
	s_waitcnt vmcnt(28)
	v_add_u32_e32 v142, 0xa0000, v149
	v_lshrrev_b32_e32 v144, 1, v142
	v_pk_fma_f32 v[28:29], s[10:11], v[28:29], v[232:233]
	v_pk_fma_f32 v[30:31], s[24:25], v[30:31], v[234:235]
	v_pk_fma_f32 v[24:25], s[10:11], v[24:25], v[228:229]
	v_pk_fma_f32 v[26:27], s[24:25], v[26:27], v[230:231]
	v_pk_fma_f32 v[20:21], s[10:11], v[20:21], v[240:241]
	v_pk_fma_f32 v[22:23], s[24:25], v[22:23], v[242:243]
	v_pk_fma_f32 v[16:17], s[10:11], v[16:17], v[236:237]
	v_pk_fma_f32 v[18:19], s[24:25], v[18:19], v[238:239]
	global_store_dwordx4 v142, v[28:31], s[52:53]
	global_store_dwordx4 v142, v[24:27], s[52:53] offset:16
	v_mul_f32_e32 v178, v29, v29
	v_fmac_f32_e32 v178, v28, v28
	v_mul_f32_e32 v245, v31, v31
	v_fmac_f32_e32 v245, v30, v30
	v_add_f32_e32 v178, v178, v245
	v_mul_f32_e32 v245, v25, v25
	v_fmac_f32_e32 v245, v24, v24
	v_add_f32_e32 v178, v245, v178
	v_mul_f32_e32 v245, v27, v27
	v_fmac_f32_e32 v245, v26, v26
	v_add_f32_e32 v178, v245, v178
	v_cvt_pk_bf16_f32 v28, v28, v29
	v_cvt_pk_bf16_f32 v29, v30, v31
	v_cvt_pk_bf16_f32 v30, v24, v25
	v_cvt_pk_bf16_f32 v31, v26, v27
	global_store_dwordx4 v144, v[28:31], s[28:29]
	global_store_dwordx4 v142, v[20:23], s[52:53] offset:512
	global_store_dwordx4 v142, v[16:19], s[52:53] offset:528
	v_mul_f32_e32 v244, v21, v21
	v_fmac_f32_e32 v244, v20, v20
	v_mul_f32_e32 v245, v23, v23
	v_fmac_f32_e32 v245, v22, v22
	v_add_f32_e32 v244, v244, v245
	v_mul_f32_e32 v245, v17, v17
	v_fmac_f32_e32 v245, v16, v16
	v_add_f32_e32 v244, v245, v244
	v_mul_f32_e32 v245, v19, v19
	v_fmac_f32_e32 v245, v18, v18
	v_add_f32_e32 v244, v245, v244
	v_add_f32_e32 v178, v178, v244
	v_cvt_pk_bf16_f32 v20, v20, v21
	v_cvt_pk_bf16_f32 v21, v22, v23
	v_cvt_pk_bf16_f32 v22, v16, v17
	v_cvt_pk_bf16_f32 v23, v18, v19
	global_store_dwordx4 v144, v[20:23], s[28:29] offset:256
	s_waitcnt vmcnt(24)
; __device__ __forceinline__ unsigned pk2(float lo, float hi) { return pg8::cvt_pk_bf16(lo, hi); }
;     __device__ __forceinline__ void operator()(const pg8::f32x4 (&acc)[2][2][4][2], const pg8::Unit& u, int wr, int wc, int fr, int fq) const {
;     ...
;             for (int m = 0; m < 4; ++m) {
;                 const size_t row = (size_t)(row0 + ai * 128 + m * 16);
;                 float s = 0.f;
; #pragma unroll
;                 for (int bj = 0; bj < 2; ++bj) {
;                     float* xp = X + row * DM + col0 + bj * 128;
;                     pg8::f32x4 x0 = *(const pg8::f32x4*)xp, x1 = *(const pg8::f32x4*)(xp + 4);
;                     x0 += acc[ai][bj][m][0] * coef; x1 += acc[ai][bj][m][1] * coef;
;                     *(pg8::f32x4*)xp = x0; *(pg8::f32x4*)(xp + 4) = x1;
;                     s += (x0[0] * x0[0] + x0[1] * x0[1]) + (x0[2] * x0[2] + x0[3] * x0[3]) + (x1[0] * x1[0] + x1[1] * x1[1]) + (x1[2] * x1[2] + x1[3] * x1[3]);
;                     u32x4 w; w.x = pk2(x0[0], x0[1]); w.y = pk2(x0[2], x0[3]); w.z = pk2(x1[0], x1[1]); w.w = pk2(x1[2], x1[3]);
;                     *(u32x4*)(XB + row * DM + col0 + bj * 128) = w;
;                 }
;                 s += __shfl_xor(s, 16); s += __shfl_xor(s, 32);
;                 if (fq == 0) ssq[row * 16 + u.pn * 4 + wc] = s;
;                 asm volatile("" ::: "memory");
	v_add_u32_e32 v142, 0xb0000, v149
	v_lshrrev_b32_e32 v144, 1, v142
	v_pk_fma_f32 v[12:13], s[10:11], v[12:13], v[154:155]
	v_pk_fma_f32 v[14:15], s[24:25], v[14:15], v[156:157]
	v_pk_fma_f32 v[8:9], s[10:11], v[8:9], v[150:151]
	v_pk_fma_f32 v[10:11], s[24:25], v[10:11], v[152:153]
	v_pk_fma_f32 v[4:5], s[10:11], v[4:5], v[162:163]
	v_pk_fma_f32 v[6:7], s[24:25], v[6:7], v[164:165]
	v_pk_fma_f32 v[0:1], s[10:11], v[0:1], v[158:159]
	v_pk_fma_f32 v[2:3], s[24:25], v[2:3], v[160:161]
	global_store_dwordx4 v142, v[12:15], s[52:53]
	global_store_dwordx4 v142, v[8:11], s[52:53] offset:16
	v_mul_f32_e32 v179, v13, v13
	v_fmac_f32_e32 v179, v12, v12
	v_mul_f32_e32 v245, v15, v15
	v_fmac_f32_e32 v245, v14, v14
	v_add_f32_e32 v179, v179, v245
	v_mul_f32_e32 v245, v9, v9
	v_fmac_f32_e32 v245, v8, v8
	v_add_f32_e32 v179, v245, v179
	v_mul_f32_e32 v245, v11, v11
	v_fmac_f32_e32 v245, v10, v10
	v_add_f32_e32 v179, v245, v179
	v_cvt_pk_bf16_f32 v12, v12, v13
	v_cvt_pk_bf16_f32 v13, v14, v15
	v_cvt_pk_bf16_f32 v14, v8, v9
	v_cvt_pk_bf16_f32 v15, v10, v11
	global_store_dwordx4 v144, v[12:15], s[28:29]
	global_store_dwordx4 v142, v[4:7], s[52:53] offset:512
	global_store_dwordx4 v142, v[0:3], s[52:53] offset:528
	v_mul_f32_e32 v244, v5, v5
	v_fmac_f32_e32 v244, v4, v4
	v_mul_f32_e32 v245, v7, v7
	v_fmac_f32_e32 v245, v6, v6
	v_add_f32_e32 v244, v244, v245
	v_mul_f32_e32 v245, v1, v1
	v_fmac_f32_e32 v245, v0, v0
	v_add_f32_e32 v244, v245, v244
	v_mul_f32_e32 v245, v3, v3
	v_fmac_f32_e32 v245, v2, v2
	v_add_f32_e32 v244, v245, v244
	v_add_f32_e32 v179, v179, v244
	v_cvt_pk_bf16_f32 v4, v4, v5
	v_cvt_pk_bf16_f32 v5, v6, v7
	v_cvt_pk_bf16_f32 v6, v0, v1
	v_cvt_pk_bf16_f32 v7, v2, v3
	global_store_dwordx4 v144, v[4:7], s[28:29] offset:256
	ds_bpermute_b32 v196, v143, v166
	ds_bpermute_b32 v197, v143, v167
	ds_bpermute_b32 v198, v143, v168
	ds_bpermute_b32 v199, v143, v169
	ds_bpermute_b32 v200, v143, v176
	ds_bpermute_b32 v201, v143, v177
	ds_bpermute_b32 v202, v143, v178
	ds_bpermute_b32 v203, v143, v179
	s_waitcnt lgkmcnt(0)
	v_add_f32_e32 v166, v166, v196
	v_add_f32_e32 v167, v167, v197
	v_add_f32_e32 v168, v168, v198
	v_add_f32_e32 v169, v169, v199
	v_add_f32_e32 v176, v176, v200
	v_add_f32_e32 v177, v177, v201
	v_add_f32_e32 v178, v178, v202
	v_add_f32_e32 v179, v179, v203
	ds_bpermute_b32 v196, v145, v166
	ds_bpermute_b32 v197, v145, v167
	ds_bpermute_b32 v198, v145, v168
	ds_bpermute_b32 v199, v145, v169
	ds_bpermute_b32 v200, v145, v176
	ds_bpermute_b32 v201, v145, v177
	ds_bpermute_b32 v202, v145, v178
	ds_bpermute_b32 v203, v145, v179
	s_waitcnt lgkmcnt(0)
	v_add_f32_e32 v166, v166, v196
	v_add_f32_e32 v167, v167, v197
	v_add_f32_e32 v168, v168, v198
	v_add_f32_e32 v169, v169, v199
	v_add_f32_e32 v176, v176, v200
	v_add_f32_e32 v177, v177, v201
	v_add_f32_e32 v178, v178, v202
	v_add_f32_e32 v179, v179, v203
	v_lshrrev_b32_e32 v144, 12, v149
	s_and_saveexec_b64 s[0:1], s[4:5]
	s_add_i32 s51, s50, 0x0
	v_lshl_add_u32 v142, v144, 6, s51
	global_store_dword v142, v166, s[30:31]
	s_add_i32 s51, s50, 0x400
	v_lshl_add_u32 v142, v144, 6, s51
	global_store_dword v142, v167, s[30:31]
	s_add_i32 s51, s50, 0x800
	v_lshl_add_u32 v142, v144, 6, s51
	global_store_dword v142, v168, s[30:31]
	s_add_i32 s51, s50, 0xc00
	v_lshl_add_u32 v142, v144, 6, s51
	global_store_dword v142, v169, s[30:31]
	s_add_i32 s51, s50, 0x2000
	v_lshl_add_u32 v142, v144, 6, s51
	global_store_dword v142, v176, s[30:31]
	s_add_i32 s51, s50, 0x2400
	v_lshl_add_u32 v142, v144, 6, s51
	global_store_dword v142, v177, s[30:31]
	s_add_i32 s51, s50, 0x2800
	v_lshl_add_u32 v142, v144, 6, s51
	global_store_dword v142, v178, s[30:31]
	s_add_i32 s51, s50, 0x2c00
	v_lshl_add_u32 v142, v144, 6, s51
	global_store_dword v142, v179, s[30:31]
